# GDN prep conv taps: weight loads of taps 1-3 issued together with tap 0 (one round trip per section), originals replaced by register moves
# speedup vs baseline: 1.0062x; 1.0062x over previous
.LBB0_760:
	s_lshr_b32 s2, s13, 2
	s_and_b32 s37, s13, 3
	v_mov_b32_e32 v106, v228
	s_bfe_u32 s8, s13, 0x60002
	s_lshl_b32 s5, s2, 6
	s_lshl_b32 s4, s37, 7
	s_cmp_lg_u32 s8, 0
	v_ashrrev_i32_e32 v104, 3, v106
	s_cselect_b64 s[8:9], -1, 0
	v_cmp_lt_i32_e32 vcc, 2, v104
	s_waitcnt vmcnt(0)
	v_add_u32_e32 v0, -3, v104
	s_or_b64 vcc, s[8:9], vcc
	v_cndmask_b32_e32 v0, 0, v0, vcc
	v_cndmask_b32_e64 v44, 0, 1.0, vcc
	v_cmp_lt_i32_e32 vcc, 1, v104
	v_add_u32_e32 v4, -2, v104
	s_or_b64 vcc, s[8:9], vcc
	v_cndmask_b32_e32 v4, 0, v4, vcc
	v_cndmask_b32_e64 v42, 0, 1.0, vcc
	v_cmp_lt_i32_e32 vcc, 0, v104
	v_add_u32_e32 v8, -1, v104
	s_or_b64 vcc, s[8:9], vcc
	v_cndmask_b32_e32 v8, 0, v8, vcc
	v_cndmask_b32_e64 v40, 0, 1.0, vcc
	v_cmp_lt_i32_e32 vcc, -1, v104
	s_movk_i32 s2, 0x110
	s_or_b64 vcc, s[8:9], vcc
	v_and_b32_e32 v105, 7, v106
	v_mul_lo_u32 v109, v104, s2
	s_movk_i32 s2, 0x410
	v_cndmask_b32_e32 v14, 0, v104, vcc
	v_lshlrev_b32_e32 v108, 4, v105
	v_mul_lo_u32 v1, v104, s2
	v_add_u32_e32 v0, s5, v0
	v_mov_b64_e32 v[12:13], s[94:95]
	v_add_u32_e32 v4, s5, v4
	v_add_u32_e32 v8, s5, v8
	v_add_u32_e32 v14, s5, v14
	v_add_u32_e32 v107, 0, v1
	v_or_b32_e32 v39, s4, v108
	v_mad_i64_i32 v[0:1], s[38:39], v0, s66, v[12:13]
	v_mad_i64_i32 v[4:5], s[38:39], v4, s66, v[12:13]
	v_mad_i64_i32 v[8:9], s[38:39], v8, s66, v[12:13]
	v_mad_i64_i32 v[12:13], s[8:9], v14, s66, v[12:13]
	v_lshl_add_u64 v[46:47], v[0:1], 0, s[26:27]
	v_lshlrev_b32_e32 v16, 1, v39
	v_lshl_add_u64 v[48:49], v[4:5], 0, s[26:27]
	v_lshl_add_u64 v[50:51], v[8:9], 0, s[26:27]
	v_lshl_add_u64 v[52:53], v[12:13], 0, s[26:27]
	v_lshl_add_u64 v[0:1], v[46:47], 0, v[16:17]
	v_lshl_add_u64 v[4:5], v[48:49], 0, v[16:17]
	v_lshl_add_u64 v[8:9], v[50:51], 0, v[16:17]
	v_lshl_add_u64 v[12:13], v[52:53], 0, v[16:17]
	flat_load_dwordx4 v[30:33], v[0:1]
	s_nop 0
	flat_load_dwordx4 v[0:3], v[0:1] offset:16
	s_nop 0
	flat_load_dwordx4 v[26:29], v[4:5]
	s_nop 0
	flat_load_dwordx4 v[4:7], v[4:5] offset:16
	s_nop 0
	flat_load_dwordx4 v[22:25], v[8:9]
	s_nop 0
	flat_load_dwordx4 v[8:11], v[8:9] offset:16
	s_nop 0
	flat_load_dwordx4 v[18:21], v[12:13]
	s_nop 0
	flat_load_dwordx4 v[12:15], v[12:13] offset:16
	s_mov_b32 s8, 0
	s_ashr_i32 s9, s8, 31
	s_lshl_b64 s[8:9], s[8:9], 3
	s_add_u32 s8, s0, s8
	s_addc_u32 s9, s1, s9
	s_load_dwordx2 s[8:9], s[8:9], 0x90
	v_lshlrev_b32_e32 v41, 2, v39
	v_cndmask_b32_e64 v38, 0, 1.0, vcc
	v_and_b32_e32 v111, 64, v234
	v_or_b32_e32 v16, 0x400, v16
	s_waitcnt lgkmcnt(0)
	s_add_u32 s98, s8, s16
	s_addc_u32 s99, s9, s17
	s_add_u32 s100, s8, s18
	s_addc_u32 s101, s9, s19
	s_add_u32 s30, s8, s22
	s_addc_u32 s31, s9, s23
	s_add_u32 s8, s8, s15
	s_addc_u32 s9, s9, s14
	global_load_dwordx4 v[34:37], v41, s[8:9] offset:48
	global_load_dwordx4 v[54:57], v41, s[8:9] offset:32
	global_load_dwordx4 v[58:61], v41, s[8:9] offset:16
	global_load_dwordx4 v[62:65], v41, s[8:9]
	global_load_dwordx4 v[140:143], v41, s[98:99] offset:48
	global_load_dwordx4 v[144:147], v41, s[98:99] offset:32
	global_load_dwordx4 v[148:151], v41, s[98:99] offset:16
	global_load_dwordx4 v[152:155], v41, s[98:99]
	global_load_dwordx4 v[156:159], v41, s[100:101] offset:48
	global_load_dwordx4 v[160:163], v41, s[100:101] offset:32
	global_load_dwordx4 v[164:167], v41, s[100:101] offset:16
	global_load_dwordx4 v[168:171], v41, s[100:101]
	global_load_dwordx4 v[172:175], v41, s[30:31] offset:48
	global_load_dwordx4 v[176:179], v41, s[30:31] offset:32
	global_load_dwordx4 v[180:183], v41, s[30:31] offset:16
	global_load_dwordx4 v[184:187], v41, s[30:31]
	s_mov_b32 s8, 0
	s_ashr_i32 s9, s8, 31
	s_lshl_b64 s[8:9], s[8:9], 3
	s_add_u32 s8, s0, s8
	s_addc_u32 s9, s1, s9
	s_load_dwordx2 s[8:9], s[8:9], 0x90
	v_lshl_add_u32 v110, v105, 6, v107
	s_waitcnt lgkmcnt(0)
	s_add_u32 s8, s8, s16
	s_addc_u32 s9, s9, s17
	s_waitcnt vmcnt(0)
	v_lshlrev_b32_e32 v43, 16, v30
	v_and_b32_e32 v30, 0xffff0000, v30
	v_lshlrev_b32_e32 v84, 16, v18
	v_and_b32_e32 v18, 0xffff0000, v18
	v_pk_mul_f32 v[58:59], v[44:45], v[58:59] op_sel_hi:[0,1]
	v_pk_mul_f32 v[62:63], v[44:45], v[62:63] op_sel_hi:[0,1]
	v_pk_mul_f32 v[64:65], v[44:45], v[64:65] op_sel_hi:[0,1]
	v_fma_f32 v82, v63, v30, 0
	v_lshlrev_b32_e32 v30, 16, v31
	v_fma_f32 v83, v62, v43, 0
	v_fma_f32 v81, v64, v30, 0
	v_and_b32_e32 v30, 0xffff0000, v31
	v_lshlrev_b32_e32 v43, 16, v32
	v_and_b32_e32 v32, 0xffff0000, v32
	v_fma_f32 v80, v65, v30, 0
	v_pk_mul_f32 v[30:31], v[44:45], v[60:61] op_sel_hi:[0,1]
	v_fma_f32 v78, v59, v32, 0
	v_lshlrev_b32_e32 v32, 16, v33
	v_fma_f32 v45, v30, v32, 0
	v_and_b32_e32 v30, 0xffff0000, v33
	v_fma_f32 v79, v58, v43, 0
	v_fma_f32 v43, v31, v30, 0
	v_pk_mul_f32 v[58:59], v[44:45], v[56:57] op_sel_hi:[0,1]
	v_pk_mul_f32 v[62:63], v[44:45], v[54:55] op_sel_hi:[0,1]
	v_pk_mul_f32 v[54:55], v[44:45], v[36:37] op_sel_hi:[0,1]
	v_pk_mul_f32 v[56:57], v[44:45], v[34:35] op_sel_hi:[0,1]
	v_mov_b64_e32 v[30:31], v[140:141]
	v_mov_b64_e32 v[32:33], v[142:143]
	v_mov_b64_e32 v[34:35], v[144:145]
	v_mov_b64_e32 v[36:37], v[146:147]
	v_mov_b64_e32 v[64:65], v[148:149]
	v_mov_b64_e32 v[66:67], v[150:151]
	v_mov_b64_e32 v[68:69], v[152:153]
	v_mov_b64_e32 v[70:71], v[154:155]
	s_mov_b32 s8, 0
	s_ashr_i32 s9, s8, 31
	s_lshl_b64 s[8:9], s[8:9], 3
	s_add_u32 s8, s0, s8
	s_addc_u32 s9, s1, s9
	s_load_dwordx2 s[8:9], s[8:9], 0x90
	s_waitcnt lgkmcnt(0)
	s_add_u32 s8, s8, s18
	s_addc_u32 s9, s9, s19
	s_waitcnt vmcnt(0)
	v_pk_mul_f32 v[60:61], v[42:43], v[70:71] op_sel_hi:[0,1]
	v_pk_mul_f32 v[68:69], v[42:43], v[68:69] op_sel_hi:[0,1]
	v_lshlrev_b32_e32 v70, 16, v26
	v_and_b32_e32 v26, 0xffff0000, v26
	v_fmac_f32_e32 v82, v69, v26
	v_lshlrev_b32_e32 v26, 16, v27
	v_fmac_f32_e32 v81, v60, v26
	v_and_b32_e32 v26, 0xffff0000, v27
	v_fmac_f32_e32 v80, v61, v26
	v_pk_mul_f32 v[60:61], v[42:43], v[64:65] op_sel_hi:[0,1]
	v_lshlrev_b32_e32 v64, 16, v28
	v_and_b32_e32 v28, 0xffff0000, v28
	v_pk_mul_f32 v[26:27], v[42:43], v[66:67] op_sel_hi:[0,1]
	v_fmac_f32_e32 v78, v61, v28
	v_lshlrev_b32_e32 v28, 16, v29
	v_fmac_f32_e32 v45, v26, v28
	v_and_b32_e32 v26, 0xffff0000, v29
	v_fmac_f32_e32 v43, v27, v26
	v_fmac_f32_e32 v83, v68, v70
	v_fmac_f32_e32 v79, v60, v64
	v_pk_mul_f32 v[66:67], v[42:43], v[36:37] op_sel_hi:[0,1]
	v_pk_mul_f32 v[70:71], v[42:43], v[34:35] op_sel_hi:[0,1]
	v_pk_mul_f32 v[60:61], v[42:43], v[32:33] op_sel_hi:[0,1]
	v_pk_mul_f32 v[64:65], v[42:43], v[30:31] op_sel_hi:[0,1]
	v_mov_b64_e32 v[26:27], v[156:157]
	v_mov_b64_e32 v[28:29], v[158:159]
	v_mov_b64_e32 v[30:31], v[160:161]
	v_mov_b64_e32 v[32:33], v[162:163]
	v_mov_b64_e32 v[34:35], v[164:165]
	v_mov_b64_e32 v[36:37], v[166:167]
	v_mov_b64_e32 v[72:73], v[168:169]
	v_mov_b64_e32 v[74:75], v[170:171]
	s_mov_b32 s8, 0
	s_ashr_i32 s9, s8, 31
	s_lshl_b64 s[8:9], s[8:9], 3
	s_add_u32 s8, s0, s8
	s_addc_u32 s9, s1, s9
	s_load_dwordx2 s[8:9], s[8:9], 0x90
	s_waitcnt lgkmcnt(0)
	s_add_u32 s8, s8, s22
	s_addc_u32 s9, s9, s23
	s_waitcnt vmcnt(2)
	v_pk_mul_f32 v[76:77], v[40:41], v[30:31] op_sel_hi:[0,1]
	s_waitcnt vmcnt(1)
	v_pk_mul_f32 v[34:35], v[40:41], v[34:35] op_sel_hi:[0,1]
	s_waitcnt vmcnt(0)
	v_pk_mul_f32 v[68:69], v[40:41], v[74:75] op_sel_hi:[0,1]
	v_pk_mul_f32 v[72:73], v[40:41], v[72:73] op_sel_hi:[0,1]
	v_lshlrev_b32_e32 v74, 16, v22
	v_and_b32_e32 v22, 0xffff0000, v22
	v_fmac_f32_e32 v82, v73, v22
	v_lshlrev_b32_e32 v22, 16, v23
	v_fmac_f32_e32 v81, v68, v22
	v_and_b32_e32 v22, 0xffff0000, v23
	v_fmac_f32_e32 v80, v69, v22
	v_pk_mul_f32 v[22:23], v[40:41], v[36:37] op_sel_hi:[0,1]
	v_lshlrev_b32_e32 v36, 16, v24
	v_and_b32_e32 v24, 0xffff0000, v24
	v_fmac_f32_e32 v78, v35, v24
	v_lshlrev_b32_e32 v24, 16, v25
	v_fmac_f32_e32 v45, v22, v24
	v_and_b32_e32 v22, 0xffff0000, v25
	v_fmac_f32_e32 v83, v72, v74
	v_fmac_f32_e32 v79, v34, v36
	v_fmac_f32_e32 v43, v23, v22
	v_pk_mul_f32 v[74:75], v[40:41], v[32:33] op_sel_hi:[0,1]
	v_pk_mul_f32 v[68:69], v[40:41], v[28:29] op_sel_hi:[0,1]
	v_pk_mul_f32 v[72:73], v[40:41], v[26:27] op_sel_hi:[0,1]
	v_mov_b64_e32 v[22:23], v[172:173]
	v_mov_b64_e32 v[24:25], v[174:175]
	v_mov_b64_e32 v[26:27], v[176:177]
	v_mov_b64_e32 v[28:29], v[178:179]
	v_mov_b64_e32 v[30:31], v[180:181]
	v_mov_b64_e32 v[32:33], v[182:183]
	v_mov_b64_e32 v[34:35], v[184:185]
	v_mov_b64_e32 v[36:37], v[186:187]
	s_waitcnt vmcnt(2)
	v_pk_mul_f32 v[26:27], v[38:39], v[26:27] op_sel_hi:[0,1]
	s_waitcnt vmcnt(1)
	v_pk_mul_f32 v[30:31], v[38:39], v[30:31] op_sel_hi:[0,1]
	s_waitcnt vmcnt(0)
	v_pk_mul_f32 v[34:35], v[38:39], v[34:35] op_sel_hi:[0,1]
	v_pk_mul_f32 v[36:37], v[38:39], v[36:37] op_sel_hi:[0,1]
	v_fmac_f32_e32 v82, v35, v18
	v_lshlrev_b32_e32 v18, 16, v19
	v_fmac_f32_e32 v81, v36, v18
	v_and_b32_e32 v18, 0xffff0000, v19
	v_fmac_f32_e32 v80, v37, v18
	v_pk_mul_f32 v[18:19], v[38:39], v[32:33] op_sel_hi:[0,1]
	v_lshlrev_b32_e32 v32, 16, v20
	v_and_b32_e32 v20, 0xffff0000, v20
	v_fmac_f32_e32 v83, v34, v84
	v_fmac_f32_e32 v78, v31, v20
	v_lshlrev_b32_e32 v20, 16, v21
	v_fmac_f32_e32 v45, v18, v20
	v_and_b32_e32 v18, 0xffff0000, v21
	v_pk_mul_f32 v[20:21], v[38:39], v[22:23] op_sel_hi:[0,1]
	v_mul_f32_e32 v22, 0xbfb8aa3b, v83
	v_exp_f32_e32 v22, v22
	v_fmac_f32_e32 v79, v30, v32
	v_fmac_f32_e32 v43, v19, v18
	v_and_b32_e32 v23, 0xffff0000, v0
	v_add_f32_e32 v22, 1.0, v22
	v_rcp_f32_e32 v22, v22
	v_pk_mul_f32 v[18:19], v[38:39], v[24:25] op_sel_hi:[0,1]
	v_and_b32_e32 v25, 0xffff0000, v4
	v_lshlrev_b32_e32 v24, 16, v4
	v_mul_f32_e32 v30, v83, v22
	v_mul_f32_e32 v22, 0xbfb8aa3b, v82
	v_exp_f32_e32 v22, v22
	v_lshlrev_b32_e32 v4, 16, v9
	v_pk_mul_f32 v[28:29], v[38:39], v[28:29] op_sel_hi:[0,1]
	v_add_f32_e32 v22, 1.0, v22
	v_rcp_f32_e32 v22, v22
	s_nop 0
	v_mul_f32_e32 v31, v82, v22
	v_mul_f32_e32 v22, 0xbfb8aa3b, v81
	v_exp_f32_e32 v22, v22
	s_nop 0
	v_add_f32_e32 v22, 1.0, v22
	v_rcp_f32_e32 v22, v22
	s_nop 0
	v_mul_f32_e32 v32, v81, v22
	v_mul_f32_e32 v22, 0xbfb8aa3b, v80
	v_exp_f32_e32 v22, v22
	s_nop 0
	v_add_f32_e32 v22, 1.0, v22
	v_rcp_f32_e32 v22, v22
	s_nop 0
	v_mul_f32_e32 v33, v80, v22
	v_mul_f32_e32 v22, 0xbfb8aa3b, v79
	v_exp_f32_e32 v22, v22
	s_nop 0
	v_add_f32_e32 v22, 1.0, v22
	v_rcp_f32_e32 v22, v22
	s_nop 0
	v_mul_f32_e32 v34, v79, v22
	v_mul_f32_e32 v22, 0xbfb8aa3b, v78
	v_exp_f32_e32 v22, v22
	s_nop 0
	v_add_f32_e32 v22, 1.0, v22
	v_rcp_f32_e32 v22, v22
	s_nop 0
	v_mul_f32_e32 v35, v78, v22
	v_mul_f32_e32 v22, 0xbfb8aa3b, v45
	v_exp_f32_e32 v22, v22
	s_nop 0
	v_add_f32_e32 v22, 1.0, v22
	v_rcp_f32_e32 v22, v22
	s_nop 0
	v_mul_f32_e32 v36, v45, v22
	v_mul_f32_e32 v22, 0xbfb8aa3b, v43
	v_exp_f32_e32 v22, v22
	s_nop 0
	v_add_f32_e32 v22, 1.0, v22
	v_rcp_f32_e32 v22, v22
	s_nop 0
	v_mul_f32_e32 v37, v43, v22
	v_lshlrev_b32_e32 v22, 16, v0
	v_pk_fma_f32 v[22:23], v[62:63], v[22:23], 0 op_sel_hi:[1,1,0]
	v_mul_f32_e32 v43, v31, v31
	v_pk_fma_f32 v[22:23], v[70:71], v[24:25], v[22:23]
	v_and_b32_e32 v25, 0xffff0000, v8
	v_lshlrev_b32_e32 v24, 16, v8
	v_pk_fma_f32 v[22:23], v[76:77], v[24:25], v[22:23]
	v_and_b32_e32 v25, 0xffff0000, v12
	v_lshlrev_b32_e32 v24, 16, v12
	v_pk_fma_f32 v[22:23], v[26:27], v[24:25], v[22:23]
	v_fmac_f32_e32 v43, v30, v30
	v_mul_f32_e32 v0, 0xbfb8aa3b, v22
	v_exp_f32_e32 v0, v0
	v_fmac_f32_e32 v43, v32, v32
	v_fmac_f32_e32 v43, v33, v33
	v_fmac_f32_e32 v43, v34, v34
	v_add_f32_e32 v0, 1.0, v0
	v_rcp_f32_e32 v24, v0
	v_mul_f32_e32 v0, 0xbfb8aa3b, v23
	v_exp_f32_e32 v0, v0
	v_fmac_f32_e32 v43, v35, v35
	v_fmac_f32_e32 v43, v36, v36
	v_fmac_f32_e32 v43, v37, v37
	v_add_f32_e32 v0, 1.0, v0
	v_rcp_f32_e32 v25, v0
	s_nop 0
	v_pk_mul_f32 v[22:23], v[22:23], v[24:25]
	s_nop 0
	v_pk_mul_f32 v[24:25], v[22:23], v[22:23]
	s_nop 0
	v_add_f32_e32 v0, v24, v43
	v_add_f32_e32 v8, v25, v0
	v_and_b32_e32 v25, 0xffff0000, v1
	v_lshlrev_b32_e32 v24, 16, v1
	v_pk_fma_f32 v[0:1], v[58:59], v[24:25], 0 op_sel_hi:[1,1,0]
	v_and_b32_e32 v25, 0xffff0000, v5
	v_lshlrev_b32_e32 v24, 16, v5
	v_pk_fma_f32 v[0:1], v[66:67], v[24:25], v[0:1]
	v_and_b32_e32 v5, 0xffff0000, v9
	v_pk_fma_f32 v[0:1], v[74:75], v[4:5], v[0:1]
	v_and_b32_e32 v5, 0xffff0000, v13
	v_lshlrev_b32_e32 v4, 16, v13
	v_pk_fma_f32 v[0:1], v[28:29], v[4:5], v[0:1]
	v_and_b32_e32 v9, 0xffff0000, v6
	v_mul_f32_e32 v4, 0xbfb8aa3b, v0
	v_mul_f32_e32 v5, 0xbfb8aa3b, v1
	v_exp_f32_e32 v4, v4
	v_exp_f32_e32 v5, v5
	v_add_f32_e32 v4, 1.0, v4
	v_add_f32_e32 v5, 1.0, v5
	v_rcp_f32_e32 v4, v4
	v_rcp_f32_e32 v5, v5
	s_nop 0
	v_pk_mul_f32 v[0:1], v[0:1], v[4:5]
	s_nop 0
	v_pk_mul_f32 v[4:5], v[0:1], v[0:1]
	s_nop 0
	v_add_f32_e32 v4, v4, v8
	v_add_f32_e32 v12, v5, v4
	v_and_b32_e32 v5, 0xffff0000, v2
	v_lshlrev_b32_e32 v4, 16, v2
	v_pk_fma_f32 v[4:5], v[56:57], v[4:5], 0 op_sel_hi:[1,1,0]
	v_lshlrev_b32_e32 v8, 16, v6
	v_pk_fma_f32 v[4:5], v[64:65], v[8:9], v[4:5]
	v_and_b32_e32 v9, 0xffff0000, v10
	v_lshlrev_b32_e32 v8, 16, v10
	v_pk_fma_f32 v[4:5], v[72:73], v[8:9], v[4:5]
	v_and_b32_e32 v9, 0xffff0000, v14
	v_lshlrev_b32_e32 v8, 16, v14
	v_pk_fma_f32 v[4:5], v[20:21], v[8:9], v[4:5]
	v_lshlrev_b32_e32 v6, 16, v11
	v_mul_f32_e32 v2, 0xbfb8aa3b, v4
	v_exp_f32_e32 v2, v2
	s_nop 0
	v_add_f32_e32 v2, 1.0, v2
	v_rcp_f32_e32 v8, v2
	v_mul_f32_e32 v2, 0xbfb8aa3b, v5
	v_exp_f32_e32 v2, v2
	s_nop 0
	v_add_f32_e32 v2, 1.0, v2
	v_rcp_f32_e32 v9, v2
	s_nop 0
	v_pk_mul_f32 v[4:5], v[4:5], v[8:9]
	s_nop 0
	v_pk_mul_f32 v[8:9], v[4:5], v[4:5]
	s_nop 0
	v_add_f32_e32 v2, v8, v12
	v_add_f32_e32 v10, v9, v2
	v_and_b32_e32 v9, 0xffff0000, v3
	v_lshlrev_b32_e32 v8, 16, v3
	v_pk_fma_f32 v[2:3], v[54:55], v[8:9], 0 op_sel_hi:[1,1,0]
	v_and_b32_e32 v9, 0xffff0000, v7
	v_lshlrev_b32_e32 v8, 16, v7
	v_pk_fma_f32 v[2:3], v[60:61], v[8:9], v[2:3]
	v_and_b32_e32 v7, 0xffff0000, v11
	v_pk_fma_f32 v[2:3], v[68:69], v[6:7], v[2:3]
	v_and_b32_e32 v7, 0xffff0000, v15
	v_lshlrev_b32_e32 v6, 16, v15
	v_pk_fma_f32 v[2:3], v[18:19], v[6:7], v[2:3]
	v_add_u32_e32 v8, 64, v111
	v_mul_f32_e32 v6, 0xbfb8aa3b, v3
	v_exp_f32_e32 v6, v6
	s_nop 0
	v_add_f32_e32 v6, 1.0, v6
	v_rcp_f32_e32 v7, v6
	v_mul_f32_e32 v6, 0xbfb8aa3b, v2
	v_exp_f32_e32 v6, v6
	s_nop 0
	v_add_f32_e32 v6, 1.0, v6
	v_rcp_f32_e32 v6, v6
	s_nop 0
	v_pk_mul_f32 v[2:3], v[2:3], v[6:7]
	s_nop 0
	v_pk_mul_f32 v[6:7], v[2:3], v[2:3]
	s_nop 0
	v_add_f32_e32 v6, v6, v10
	v_add_f32_e32 v6, v7, v6
	v_xor_b32_e32 v7, 1, v234
	v_cmp_lt_i32_e32 vcc, v7, v8
	s_nop 1
	v_cndmask_b32_e32 v7, v234, v7, vcc
	v_lshlrev_b32_e32 v45, 2, v7
	ds_bpermute_b32 v7, v45, v6
	s_waitcnt lgkmcnt(0)
	v_add_f32_e32 v6, v6, v7
	v_xor_b32_e32 v7, 2, v234
	v_cmp_lt_i32_e32 vcc, v7, v8
	s_nop 1
	v_cndmask_b32_e32 v7, v234, v7, vcc
	v_lshlrev_b32_e32 v112, 2, v7
	ds_bpermute_b32 v7, v112, v6
	s_waitcnt lgkmcnt(0)
	v_add_f32_e32 v6, v6, v7
	v_xor_b32_e32 v7, 4, v234
	v_cmp_lt_i32_e32 vcc, v7, v8
	s_nop 1
	v_cndmask_b32_e32 v7, v234, v7, vcc
	v_lshlrev_b32_e32 v113, 2, v7
	ds_bpermute_b32 v7, v113, v6
	s_waitcnt lgkmcnt(0)
	v_add_f32_e32 v6, v6, v7
	v_add_f32_e32 v6, 0x358637bd, v6
	v_cmp_gt_f32_e32 vcc, s33, v6
	v_mul_f32_e32 v7, 0x4b800000, v6
	s_nop 0
	v_cndmask_b32_e32 v6, v6, v7, vcc
	v_rsq_f32_e32 v6, v6
	s_nop 0
	v_mul_f32_e32 v7, 0x45800000, v6
	v_cndmask_b32_e32 v6, v6, v7, vcc
	v_mul_f32_e32 v6, 0x3db504f3, v6
	v_mul_f32_e32 v7, v30, v6
	v_mul_f32_e32 v8, v31, v6
	v_mul_f32_e32 v9, v32, v6
	v_mul_f32_e32 v10, v33, v6
	v_mul_f32_e32 v11, v34, v6
	v_mul_f32_e32 v12, v35, v6
	v_mul_f32_e32 v13, v36, v6
	v_mul_f32_e32 v14, v37, v6
	v_mul_f32_e32 v15, v22, v6
	v_mul_f32_e32 v18, v23, v6
	v_mul_f32_e32 v0, v0, v6
	v_mul_f32_e32 v1, v1, v6
	v_mul_f32_e32 v4, v4, v6
	v_mul_f32_e32 v5, v5, v6
	v_mul_f32_e32 v2, v2, v6
	v_mul_f32_e32 v3, v3, v6
	v_lshlrev_b32_e32 v6, 5, v105
	v_add3_u32 v43, 0, v6, v109
	v_cvt_pk_bf16_f32 v6, v7, v8
	v_add_u32_e32 v8, 0x4400, v43
	v_cvt_pk_bf16_f32 v7, v9, v10
	ds_write2_b32 v8, v6, v7 offset1:1
	v_cvt_pk_bf16_f32 v6, v11, v12
	v_cvt_pk_bf16_f32 v0, v0, v1
	v_cvt_pk_bf16_f32 v7, v13, v14
	ds_write2_b32 v8, v6, v7 offset0:2 offset1:3
	v_cvt_pk_bf16_f32 v6, v15, v18
	ds_write2_b32 v8, v6, v0 offset0:4 offset1:5
	v_cvt_pk_bf16_f32 v0, v4, v5
	v_cvt_pk_bf16_f32 v1, v2, v3
	ds_write2_b32 v8, v0, v1 offset0:6 offset1:7
	v_lshl_add_u64 v[0:1], v[46:47], 0, v[16:17]
	flat_load_dwordx4 v[30:33], v[0:1]
	flat_load_dwordx4 v[12:15], v[0:1] offset:16
	v_lshl_add_u64 v[0:1], v[48:49], 0, v[16:17]
	flat_load_dwordx4 v[26:29], v[0:1]
	flat_load_dwordx4 v[8:11], v[0:1] offset:16
	v_lshl_add_u64 v[0:1], v[50:51], 0, v[16:17]
	flat_load_dwordx4 v[22:25], v[0:1]
	flat_load_dwordx4 v[4:7], v[0:1] offset:16
	v_lshl_add_u64 v[0:1], v[52:53], 0, v[16:17]
	flat_load_dwordx4 v[18:21], v[0:1]
	s_nop 0
	flat_load_dwordx4 v[0:3], v[0:1] offset:16
	s_mov_b32 s8, 0
	s_ashr_i32 s9, s8, 31
	s_lshl_b64 s[8:9], s[8:9], 3
	s_add_u32 s8, s0, s8
	s_addc_u32 s9, s1, s9
	s_load_dwordx2 s[8:9], s[8:9], 0x90
	s_waitcnt lgkmcnt(0)
	s_add_u32 s98, s8, s16
	s_addc_u32 s99, s9, s17
	s_add_u32 s100, s8, s18
	s_addc_u32 s101, s9, s19
	s_add_u32 s30, s8, s22
	s_addc_u32 s31, s9, s23
	s_add_u32 s8, s8, s15
	s_addc_u32 s9, s9, s14
	global_load_dwordx4 v[58:61], v41, s[8:9] offset:2096
	global_load_dwordx4 v[62:65], v41, s[8:9] offset:2080
	global_load_dwordx4 v[34:37], v41, s[8:9] offset:2064
	global_load_dwordx4 v[54:57], v41, s[8:9] offset:2048
	global_load_dwordx4 v[140:143], v41, s[98:99] offset:2096
	global_load_dwordx4 v[144:147], v41, s[98:99] offset:2080
	global_load_dwordx4 v[148:151], v41, s[98:99] offset:2064
	global_load_dwordx4 v[152:155], v41, s[98:99] offset:2048
	global_load_dwordx4 v[156:159], v41, s[100:101] offset:2096
	global_load_dwordx4 v[160:163], v41, s[100:101] offset:2080
	global_load_dwordx4 v[164:167], v41, s[100:101] offset:2064
	global_load_dwordx4 v[168:171], v41, s[100:101] offset:2048
	global_load_dwordx4 v[172:175], v41, s[30:31] offset:2096
	global_load_dwordx4 v[176:179], v41, s[30:31] offset:2080
	global_load_dwordx4 v[180:183], v41, s[30:31] offset:2064
	global_load_dwordx4 v[184:187], v41, s[30:31] offset:2048
	s_mov_b32 s8, 0
	s_ashr_i32 s9, s8, 31
	s_lshl_b64 s[8:9], s[8:9], 3
	s_add_u32 s8, s0, s8
	s_addc_u32 s9, s1, s9
	s_load_dwordx2 s[8:9], s[8:9], 0x90
	s_waitcnt lgkmcnt(0)
	s_add_u32 s8, s8, s16
	s_addc_u32 s9, s9, s17
	s_waitcnt vmcnt(0)
	v_pk_mul_f32 v[92:93], v[44:45], v[60:61] op_sel_hi:[0,1]
	v_pk_mul_f32 v[74:75], v[44:45], v[58:59] op_sel_hi:[0,1]
	v_pk_mul_f32 v[66:67], v[44:45], v[34:35] op_sel_hi:[0,1]
	v_pk_mul_f32 v[78:79], v[44:45], v[54:55] op_sel_hi:[0,1]
	v_pk_mul_f32 v[34:35], v[44:45], v[64:65] op_sel_hi:[0,1]
	v_pk_mul_f32 v[54:55], v[44:45], v[62:63] op_sel_hi:[0,1]
	v_mov_b64_e32 v[82:83], v[140:141]
	v_mov_b64_e32 v[84:85], v[142:143]
	v_mov_b64_e32 v[58:59], v[144:145]
	v_mov_b64_e32 v[60:61], v[146:147]
	v_mov_b64_e32 v[88:89], v[148:149]
	v_mov_b64_e32 v[90:91], v[150:151]
	v_mov_b64_e32 v[62:63], v[152:153]
	v_mov_b64_e32 v[64:65], v[154:155]
	s_mov_b32 s8, 0
	s_ashr_i32 s9, s8, 31
	s_lshl_b64 s[8:9], s[8:9], 3
	s_add_u32 s8, s0, s8
	s_addc_u32 s9, s1, s9
	s_load_dwordx2 s[8:9], s[8:9], 0x90
	v_pk_mul_f32 v[70:71], v[44:45], v[56:57] op_sel_hi:[0,1]
	v_pk_mul_f32 v[56:57], v[44:45], v[36:37] op_sel_hi:[0,1]
	s_waitcnt lgkmcnt(0)
	s_add_u32 s8, s8, s18
	s_addc_u32 s9, s9, s19
	v_mov_b64_e32 v[100:101], v[156:157]
	v_mov_b64_e32 v[102:103], v[158:159]
	v_mov_b64_e32 v[114:115], v[160:161]
	v_mov_b64_e32 v[116:117], v[162:163]
	v_mov_b64_e32 v[118:119], v[164:165]
	v_mov_b64_e32 v[120:121], v[166:167]
	v_mov_b64_e32 v[94:95], v[168:169]
	v_mov_b64_e32 v[96:97], v[170:171]
	s_mov_b32 s8, 0
	s_ashr_i32 s9, s8, 31
	s_lshl_b64 s[8:9], s[8:9], 3
	s_add_u32 s8, s0, s8
	s_addc_u32 s9, s1, s9
	s_load_dwordx2 s[8:9], s[8:9], 0x90
	s_waitcnt lgkmcnt(0)
	s_add_u32 s8, s8, s22
	s_addc_u32 s9, s9, s23
	s_waitcnt vmcnt(7)
	v_pk_mul_f32 v[98:99], v[42:43], v[84:85] op_sel_hi:[0,1]
	s_waitcnt vmcnt(6)
	v_pk_mul_f32 v[36:37], v[42:43], v[60:61] op_sel_hi:[0,1]
	v_pk_mul_f32 v[60:61], v[42:43], v[58:59] op_sel_hi:[0,1]
	s_waitcnt vmcnt(4)
	v_pk_mul_f32 v[80:81], v[42:43], v[64:65] op_sel_hi:[0,1]
	v_pk_mul_f32 v[84:85], v[42:43], v[82:83] op_sel_hi:[0,1]
	v_pk_mul_f32 v[86:87], v[42:43], v[62:63] op_sel_hi:[0,1]
	v_pk_mul_f32 v[62:63], v[42:43], v[90:91] op_sel_hi:[0,1]
	v_pk_mul_f32 v[72:73], v[42:43], v[88:89] op_sel_hi:[0,1]
	s_waitcnt vmcnt(3)
	v_pk_mul_f32 v[130:131], v[40:41], v[100:101] op_sel_hi:[0,1]
	s_waitcnt vmcnt(2)
	v_pk_mul_f32 v[58:59], v[40:41], v[116:117] op_sel_hi:[0,1]
	s_waitcnt vmcnt(1)
	v_pk_mul_f32 v[68:69], v[40:41], v[120:121] op_sel_hi:[0,1]
	v_pk_mul_f32 v[82:83], v[40:41], v[118:119] op_sel_hi:[0,1]
	v_pk_mul_f32 v[64:65], v[40:41], v[114:115] op_sel_hi:[0,1]
	v_mov_b64_e32 v[114:115], v[172:173]
	v_mov_b64_e32 v[116:117], v[174:175]
	v_mov_b64_e32 v[118:119], v[176:177]
	v_mov_b64_e32 v[120:121], v[178:179]
	v_mov_b64_e32 v[122:123], v[180:181]
	v_mov_b64_e32 v[124:125], v[182:183]
	v_mov_b64_e32 v[126:127], v[184:185]
	v_mov_b64_e32 v[128:129], v[186:187]
	v_pk_mul_f32 v[102:103], v[40:41], v[102:103] op_sel_hi:[0,1]
	s_waitcnt vmcnt(4)
	v_pk_mul_f32 v[88:89], v[40:41], v[96:97] op_sel_hi:[0,1]
	v_pk_mul_f32 v[96:97], v[40:41], v[94:95] op_sel_hi:[0,1]
	s_waitcnt vmcnt(3)
	v_pk_mul_f32 v[114:115], v[38:39], v[114:115] op_sel_hi:[0,1]
	s_waitcnt vmcnt(2)
	v_pk_mul_f32 v[90:91], v[38:39], v[118:119] op_sel_hi:[0,1]
	v_and_b32_e32 v119, 0xffff0000, v14
	v_lshlrev_b32_e32 v118, 16, v14
	v_pk_fma_f32 v[74:75], v[74:75], v[118:119], 0 op_sel_hi:[1,1,0]
	v_and_b32_e32 v119, 0xffff0000, v10
	v_lshlrev_b32_e32 v118, 16, v10
	v_pk_fma_f32 v[74:75], v[84:85], v[118:119], v[74:75]
	v_and_b32_e32 v85, 0xffff0000, v6
	v_lshlrev_b32_e32 v84, 16, v6
	v_pk_fma_f32 v[74:75], v[130:131], v[84:85], v[74:75]
	v_and_b32_e32 v85, 0xffff0000, v2
	v_lshlrev_b32_e32 v84, 16, v2
	v_pk_fma_f32 v[74:75], v[114:115], v[84:85], v[74:75]
	v_and_b32_e32 v115, 0xffff0000, v15
	v_mul_f32_e32 v2, 0xbfb8aa3b, v74
	v_exp_f32_e32 v2, v2
	v_lshlrev_b32_e32 v114, 16, v15
	v_pk_fma_f32 v[14:15], v[92:93], v[114:115], 0 op_sel_hi:[1,1,0]
	v_and_b32_e32 v93, 0xffff0000, v11
	v_add_f32_e32 v2, 1.0, v2
	v_rcp_f32_e32 v84, v2
	v_mul_f32_e32 v2, 0xbfb8aa3b, v75
	v_exp_f32_e32 v2, v2
	v_lshlrev_b32_e32 v92, 16, v11
	v_pk_fma_f32 v[10:11], v[98:99], v[92:93], v[14:15]
	v_and_b32_e32 v15, 0xffff0000, v7
	v_lshlrev_b32_e32 v14, 16, v7
	v_pk_mul_f32 v[116:117], v[38:39], v[116:117] op_sel_hi:[0,1]
	v_add_f32_e32 v2, 1.0, v2
	v_pk_fma_f32 v[6:7], v[102:103], v[14:15], v[10:11]
	v_and_b32_e32 v11, 0xffff0000, v3
	v_lshlrev_b32_e32 v10, 16, v3
	v_rcp_f32_e32 v85, v2
	v_pk_fma_f32 v[2:3], v[116:117], v[10:11], v[6:7]
	v_lshlrev_b32_e32 v10, 16, v30
	v_and_b32_e32 v11, 0xffff0000, v30
	v_lshlrev_b32_e32 v30, 16, v31
	v_and_b32_e32 v31, 0xffff0000, v31
	v_pk_fma_f32 v[10:11], v[78:79], v[10:11], 0 op_sel_hi:[1,1,0]
	v_lshlrev_b32_e32 v14, 16, v26
	v_and_b32_e32 v15, 0xffff0000, v26
	v_pk_fma_f32 v[30:31], v[70:71], v[30:31], 0 op_sel_hi:[1,1,0]
	v_lshlrev_b32_e32 v26, 16, v27
	v_and_b32_e32 v27, 0xffff0000, v27
	v_pk_fma_f32 v[10:11], v[86:87], v[14:15], v[10:11]
	v_lshlrev_b32_e32 v14, 16, v22
	v_and_b32_e32 v15, 0xffff0000, v22
	v_pk_fma_f32 v[26:27], v[80:81], v[26:27], v[30:31]
	v_lshlrev_b32_e32 v22, 16, v23
	v_and_b32_e32 v23, 0xffff0000, v23
	s_waitcnt vmcnt(0)
	v_pk_mul_f32 v[128:129], v[38:39], v[128:129] op_sel_hi:[0,1]
	v_pk_fma_f32 v[10:11], v[96:97], v[14:15], v[10:11]
	v_lshlrev_b32_e32 v14, 16, v18
	v_and_b32_e32 v15, 0xffff0000, v18
	v_pk_fma_f32 v[22:23], v[88:89], v[22:23], v[26:27]
	v_lshlrev_b32_e32 v18, 16, v19
	v_and_b32_e32 v19, 0xffff0000, v19
	v_pk_fma_f32 v[18:19], v[128:129], v[18:19], v[22:23]
	v_lshlrev_b32_e32 v26, 16, v32
	v_mul_f32_e32 v16, 0xbfb8aa3b, v18
	v_exp_f32_e32 v16, v16
	v_and_b32_e32 v27, 0xffff0000, v32
	v_pk_fma_f32 v[26:27], v[66:67], v[26:27], 0 op_sel_hi:[1,1,0]
	v_lshlrev_b32_e32 v30, 16, v28
	v_add_f32_e32 v16, 1.0, v16
	v_rcp_f32_e32 v22, v16
	v_mul_f32_e32 v16, 0xbfb8aa3b, v19
	v_exp_f32_e32 v16, v16
	v_and_b32_e32 v31, 0xffff0000, v28
	v_pk_fma_f32 v[26:27], v[72:73], v[30:31], v[26:27]
	v_lshlrev_b32_e32 v30, 16, v24
	v_and_b32_e32 v31, 0xffff0000, v24
	v_pk_mul_f32 v[100:101], v[38:39], v[122:123] op_sel_hi:[0,1]
	v_pk_fma_f32 v[26:27], v[82:83], v[30:31], v[26:27]
	v_lshlrev_b32_e32 v30, 16, v20
	v_and_b32_e32 v31, 0xffff0000, v20
	v_add_f32_e32 v16, 1.0, v16
	v_pk_fma_f32 v[26:27], v[100:101], v[30:31], v[26:27]
	v_rcp_f32_e32 v23, v16
	v_mul_f32_e32 v16, 0xbfb8aa3b, v26
	v_lshlrev_b32_e32 v32, 16, v33
	v_and_b32_e32 v33, 0xffff0000, v33
	v_exp_f32_e32 v16, v16
	v_pk_fma_f32 v[32:33], v[56:57], v[32:33], 0 op_sel_hi:[1,1,0]
	v_lshlrev_b32_e32 v28, 16, v29
	v_and_b32_e32 v29, 0xffff0000, v29
	v_pk_fma_f32 v[28:29], v[62:63], v[28:29], v[32:33]
	v_lshlrev_b32_e32 v24, 16, v25
	v_and_b32_e32 v25, 0xffff0000, v25
	v_pk_fma_f32 v[24:25], v[68:69], v[24:25], v[28:29]
	v_lshlrev_b32_e32 v28, 16, v12
	v_and_b32_e32 v29, 0xffff0000, v12
	v_pk_fma_f32 v[28:29], v[54:55], v[28:29], 0 op_sel_hi:[1,1,0]
	v_lshlrev_b32_e32 v32, 16, v8
	v_and_b32_e32 v33, 0xffff0000, v8
	v_add_f32_e32 v16, 1.0, v16
	v_pk_fma_f32 v[28:29], v[60:61], v[32:33], v[28:29]
	v_lshlrev_b32_e32 v32, 16, v4
	v_and_b32_e32 v33, 0xffff0000, v4
	v_rcp_f32_e32 v30, v16
	v_mul_f32_e32 v16, 0xbfb8aa3b, v27
	v_pk_fma_f32 v[28:29], v[64:65], v[32:33], v[28:29]
	v_lshlrev_b32_e32 v32, 16, v0
	v_and_b32_e32 v33, 0xffff0000, v0
	v_exp_f32_e32 v16, v16
	v_pk_fma_f32 v[28:29], v[90:91], v[32:33], v[28:29]
	v_pk_mul_f32 v[94:95], v[38:39], v[124:125] op_sel_hi:[0,1]
	v_mul_f32_e32 v0, 0xbfb8aa3b, v28
	v_exp_f32_e32 v0, v0
	v_lshlrev_b32_e32 v20, 16, v21
	v_and_b32_e32 v21, 0xffff0000, v21
	v_pk_mul_f32 v[126:127], v[38:39], v[126:127] op_sel_hi:[0,1]
	v_add_f32_e32 v16, 1.0, v16
	v_pk_fma_f32 v[20:21], v[94:95], v[20:21], v[24:25]
	v_pk_fma_f32 v[10:11], v[126:127], v[14:15], v[10:11]
	v_rcp_f32_e32 v31, v16
	v_mul_f32_e32 v16, 0xbfb8aa3b, v20
	v_mul_f32_e32 v14, 0xbfb8aa3b, v10
	v_mul_f32_e32 v15, 0xbfb8aa3b, v11
	v_exp_f32_e32 v16, v16
	v_add_f32_e32 v0, 1.0, v0
	v_exp_f32_e32 v14, v14
	v_exp_f32_e32 v15, v15
	v_rcp_f32_e32 v32, v0
	v_mul_f32_e32 v0, 0xbfb8aa3b, v29
	v_exp_f32_e32 v0, v0
	v_add_f32_e32 v16, 1.0, v16
	v_lshlrev_b32_e32 v12, 16, v13
	v_and_b32_e32 v13, 0xffff0000, v13
	v_add_f32_e32 v14, 1.0, v14
	v_add_f32_e32 v15, 1.0, v15
	v_rcp_f32_e32 v24, v16
	v_mul_f32_e32 v16, 0xbfb8aa3b, v21
	v_pk_fma_f32 v[12:13], v[34:35], v[12:13], 0 op_sel_hi:[1,1,0]
	v_lshlrev_b32_e32 v8, 16, v9
	v_and_b32_e32 v9, 0xffff0000, v9
	v_rcp_f32_e32 v14, v14
	v_rcp_f32_e32 v15, v15
	v_exp_f32_e32 v16, v16
	v_add_f32_e32 v0, 1.0, v0
	v_pk_fma_f32 v[8:9], v[36:37], v[8:9], v[12:13]
	v_lshlrev_b32_e32 v4, 16, v5
	v_and_b32_e32 v5, 0xffff0000, v5
	v_pk_mul_f32 v[76:77], v[38:39], v[120:121] op_sel_hi:[0,1]
	v_mul_f32_e32 v6, 0xbfb8aa3b, v3
	v_rcp_f32_e32 v33, v0
	v_pk_fma_f32 v[4:5], v[58:59], v[4:5], v[8:9]
	v_lshlrev_b32_e32 v0, 16, v1
	v_and_b32_e32 v1, 0xffff0000, v1
	v_exp_f32_e32 v6, v6
	v_pk_fma_f32 v[0:1], v[76:77], v[0:1], v[4:5]
	v_pk_mul_f32 v[10:11], v[10:11], v[14:15]
	v_mul_f32_e32 v4, 0xbfb8aa3b, v0
	v_mul_f32_e32 v5, 0xbfb8aa3b, v1
	v_add_f32_e32 v16, 1.0, v16
	v_exp_f32_e32 v4, v4
	v_exp_f32_e32 v5, v5
	v_pk_mul_f32 v[14:15], v[10:11], v[10:11]
	v_pk_mul_f32 v[18:19], v[18:19], v[22:23]
	v_rcp_f32_e32 v25, v16
	v_add_f32_e32 v6, 1.0, v6
	v_pk_mul_f32 v[22:23], v[18:19], v[18:19]
	v_add_f32_e32 v8, v14, v15
	v_rcp_f32_e32 v7, v6
	v_mul_f32_e32 v6, 0xbfb8aa3b, v2
	v_pk_mul_f32 v[26:27], v[26:27], v[30:31]
	v_add_f32_e32 v8, v22, v8
	v_exp_f32_e32 v6, v6
	v_pk_mul_f32 v[30:31], v[26:27], v[26:27]
	v_add_f32_e32 v4, 1.0, v4
	v_add_f32_e32 v5, 1.0, v5
	v_add_f32_e32 v8, v23, v8
	v_pk_mul_f32 v[20:21], v[20:21], v[24:25]
	v_rcp_f32_e32 v4, v4
	v_rcp_f32_e32 v5, v5
	v_add_f32_e32 v8, v30, v8
	v_pk_mul_f32 v[24:25], v[20:21], v[20:21]
	v_add_f32_e32 v8, v31, v8
	v_pk_mul_f32 v[28:29], v[28:29], v[32:33]
	v_add_f32_e32 v8, v24, v8
	v_add_f32_e32 v6, 1.0, v6
	v_pk_mul_f32 v[32:33], v[28:29], v[28:29]
	v_add_f32_e32 v8, v25, v8
	v_rcp_f32_e32 v6, v6
	v_pk_mul_f32 v[0:1], v[0:1], v[4:5]
	v_add_f32_e32 v8, v32, v8
	v_pk_mul_f32 v[4:5], v[0:1], v[0:1]
	v_add_f32_e32 v8, v33, v8
	v_pk_mul_f32 v[74:75], v[74:75], v[84:85]
	v_add_f32_e32 v4, v4, v8
	v_pk_mul_f32 v[84:85], v[74:75], v[74:75]
	v_add_f32_e32 v4, v5, v4
	v_pk_mul_f32 v[2:3], v[2:3], v[6:7]
	v_add_f32_e32 v4, v84, v4
	v_pk_mul_f32 v[6:7], v[2:3], v[2:3]
	v_add_f32_e32 v4, v85, v4
	v_add_f32_e32 v4, v6, v4
	v_add_f32_e32 v4, v7, v4
	ds_bpermute_b32 v5, v45, v4
	v_or_b32_e32 v34, 0x400, v39
	s_waitcnt lgkmcnt(0)
	v_add_f32_e32 v4, v4, v5
	ds_bpermute_b32 v5, v112, v4
	s_waitcnt lgkmcnt(0)
	v_add_f32_e32 v4, v4, v5
	ds_bpermute_b32 v5, v113, v4
	s_waitcnt lgkmcnt(0)
	v_add_f32_e32 v4, v4, v5
	v_add_f32_e32 v4, 0x358637bd, v4
	v_cmp_gt_f32_e32 vcc, s33, v4
	v_mul_f32_e32 v5, 0x4b800000, v4
	s_nop 0
	v_cndmask_b32_e32 v4, v4, v5, vcc
	v_rsq_f32_e32 v4, v4
	s_nop 0
	v_mul_f32_e32 v5, 0x45800000, v4
	v_cndmask_b32_e32 v16, v4, v5, vcc
	v_pk_mul_f32 v[4:5], v[10:11], v[16:17] op_sel_hi:[1,0]
	v_pk_mul_f32 v[6:7], v[18:19], v[16:17] op_sel_hi:[1,0]
	v_pk_mul_f32 v[8:9], v[26:27], v[16:17] op_sel_hi:[1,0]
	v_pk_mul_f32 v[10:11], v[20:21], v[16:17] op_sel_hi:[1,0]
	v_pk_mul_f32 v[12:13], v[28:29], v[16:17] op_sel_hi:[1,0]
	v_pk_mul_f32 v[14:15], v[0:1], v[16:17] op_sel_hi:[1,0]
	v_pk_mul_f32 v[0:1], v[74:75], v[16:17] op_sel_hi:[1,0]
	v_pk_mul_f32 v[2:3], v[2:3], v[16:17] op_sel_hi:[1,0]
	v_cvt_pk_bf16_f32 v16, v4, v5
	v_cvt_pk_bf16_f32 v18, v6, v7
	ds_write2_b32 v43, v16, v18 offset1:1
	v_cvt_pk_bf16_f32 v16, v8, v9
	v_cvt_pk_bf16_f32 v18, v10, v11
	ds_write2_b32 v43, v16, v18 offset0:2 offset1:3
	v_cvt_pk_bf16_f32 v16, v12, v13
	v_cvt_pk_bf16_f32 v18, v14, v15
	ds_write2_b32 v43, v16, v18 offset0:4 offset1:5
	v_cvt_pk_bf16_f32 v16, v0, v1
	v_cvt_pk_bf16_f32 v18, v2, v3
	ds_write2_b32 v43, v16, v18 offset0:6 offset1:7
	ds_write_b128 v110, v[4:7] offset:35328
	ds_write_b128 v110, v[8:11] offset:35344
	ds_write_b128 v110, v[12:15] offset:35360
	ds_write_b128 v110, v[0:3] offset:35376
	v_lshlrev_b32_e32 v16, 1, v34
	v_lshl_add_u64 v[0:1], v[46:47], 0, v[16:17]
	flat_load_dwordx4 v[12:15], v[0:1]
	flat_load_dwordx4 v[30:33], v[0:1] offset:16
	v_lshl_add_u64 v[0:1], v[48:49], 0, v[16:17]
	flat_load_dwordx4 v[8:11], v[0:1]
	flat_load_dwordx4 v[26:29], v[0:1] offset:16
	v_lshl_add_u64 v[0:1], v[50:51], 0, v[16:17]
	v_lshl_add_u64 v[18:19], v[52:53], 0, v[16:17]
	flat_load_dwordx4 v[4:7], v[0:1]
	flat_load_dwordx4 v[22:25], v[0:1] offset:16
	s_nop 0
	flat_load_dwordx4 v[0:3], v[18:19]
	s_nop 0
	flat_load_dwordx4 v[18:21], v[18:19] offset:16
	s_mov_b32 s8, 0
	s_ashr_i32 s9, s8, 31
	s_lshl_b64 s[8:9], s[8:9], 3
	s_add_u32 s8, s0, s8
	s_addc_u32 s9, s1, s9
	s_load_dwordx2 s[8:9], s[8:9], 0x90
	v_lshlrev_b32_e32 v16, 2, v34
	v_cmp_gt_u32_e32 vcc, 64, v106
	s_waitcnt lgkmcnt(0)
	s_add_u32 s98, s8, s16
	s_addc_u32 s99, s9, s17
	s_add_u32 s100, s8, s18
	s_addc_u32 s101, s9, s19
	s_add_u32 s30, s8, s22
	s_addc_u32 s31, s9, s23
	s_add_u32 s8, s8, s15
	s_addc_u32 s9, s9, s14
	global_load_dwordx4 v[52:55], v16, s[8:9] offset:48
	global_load_dwordx4 v[56:59], v16, s[8:9] offset:32
	global_load_dwordx4 v[48:51], v16, s[8:9] offset:16
	global_load_dwordx4 v[34:37], v16, s[8:9]
	global_load_dwordx4 v[140:143], v16, s[98:99] offset:48
	global_load_dwordx4 v[144:147], v16, s[98:99] offset:32
	global_load_dwordx4 v[148:151], v16, s[98:99] offset:16
	global_load_dwordx4 v[152:155], v16, s[98:99]
	global_load_dwordx4 v[156:159], v16, s[100:101] offset:48
	global_load_dwordx4 v[160:163], v16, s[100:101] offset:32
	global_load_dwordx4 v[164:167], v16, s[100:101] offset:16
	global_load_dwordx4 v[168:171], v16, s[100:101]
	global_load_dwordx4 v[172:175], v16, s[30:31] offset:48
	global_load_dwordx4 v[176:179], v16, s[30:31] offset:32
	global_load_dwordx4 v[180:183], v16, s[30:31] offset:16
	global_load_dwordx4 v[184:187], v16, s[30:31]
	s_mov_b32 s8, 0
	s_ashr_i32 s9, s8, 31
	s_lshl_b64 s[8:9], s[8:9], 3
	s_add_u32 s8, s0, s8
	s_addc_u32 s9, s1, s9
	s_load_dwordx2 s[8:9], s[8:9], 0x90
	s_waitcnt lgkmcnt(0)
	s_add_u32 s8, s8, s16
	s_addc_u32 s9, s9, s17
	s_waitcnt vmcnt(0)
	v_pk_mul_f32 v[70:71], v[44:45], v[52:53] op_sel_hi:[0,1]
	v_pk_mul_f32 v[56:57], v[44:45], v[56:57] op_sel_hi:[0,1]
	v_pk_mul_f32 v[48:49], v[44:45], v[48:49] op_sel_hi:[0,1]
	v_pk_mul_f32 v[34:35], v[44:45], v[34:35] op_sel_hi:[0,1]
	v_pk_mul_f32 v[36:37], v[44:45], v[36:37] op_sel_hi:[0,1]
	v_pk_mul_f32 v[50:51], v[44:45], v[50:51] op_sel_hi:[0,1]
	v_pk_mul_f32 v[62:63], v[44:45], v[58:59] op_sel_hi:[0,1]
	v_pk_mul_f32 v[78:79], v[44:45], v[54:55] op_sel_hi:[0,1]
	v_mov_b64_e32 v[66:67], v[140:141]
	v_mov_b64_e32 v[68:69], v[142:143]
	v_mov_b64_e32 v[72:73], v[144:145]
	v_mov_b64_e32 v[74:75], v[146:147]
	v_mov_b64_e32 v[58:59], v[148:149]
	v_mov_b64_e32 v[60:61], v[150:151]
	v_mov_b64_e32 v[44:45], v[152:153]
	v_mov_b64_e32 v[46:47], v[154:155]
	s_mov_b32 s8, 0
	s_ashr_i32 s9, s8, 31
	s_lshl_b64 s[8:9], s[8:9], 3
	s_add_u32 s8, s0, s8
	s_addc_u32 s9, s1, s9
	s_load_dwordx2 s[8:9], s[8:9], 0x90
	s_waitcnt lgkmcnt(0)
	s_add_u32 s8, s8, s18
	s_addc_u32 s9, s9, s19
	s_waitcnt vmcnt(3)
	v_pk_mul_f32 v[80:81], v[42:43], v[66:67] op_sel_hi:[0,1]
	s_waitcnt vmcnt(2)
	v_pk_mul_f32 v[64:65], v[42:43], v[72:73] op_sel_hi:[0,1]
	v_pk_mul_f32 v[72:73], v[42:43], v[74:75] op_sel_hi:[0,1]
	v_pk_mul_f32 v[86:87], v[42:43], v[68:69] op_sel_hi:[0,1]
	v_mov_b64_e32 v[88:89], v[156:157]
	v_mov_b64_e32 v[90:91], v[158:159]
	v_mov_b64_e32 v[74:75], v[160:161]
	v_mov_b64_e32 v[76:77], v[162:163]
	v_mov_b64_e32 v[66:67], v[164:165]
	v_mov_b64_e32 v[68:69], v[166:167]
	v_mov_b64_e32 v[82:83], v[168:169]
	v_mov_b64_e32 v[84:85], v[170:171]
	s_mov_b32 s8, 0
	s_ashr_i32 s9, s8, 31
	s_lshl_b64 s[8:9], s[8:9], 3
	s_add_u32 s8, s0, s8
	s_addc_u32 s9, s1, s9
	s_load_dwordx2 s[8:9], s[8:9], 0x90
	s_waitcnt vmcnt(4)
	v_pk_mul_f32 v[44:45], v[42:43], v[44:45] op_sel_hi:[0,1]
	v_pk_mul_f32 v[46:47], v[42:43], v[46:47] op_sel_hi:[0,1]
	v_pk_mul_f32 v[54:55], v[42:43], v[58:59] op_sel_hi:[0,1]
	v_pk_mul_f32 v[58:59], v[42:43], v[60:61] op_sel_hi:[0,1]
	s_waitcnt lgkmcnt(0)
	s_add_u32 s8, s8, s22
	s_addc_u32 s9, s9, s23
	v_mov_b64_e32 v[92:93], v[172:173]
	v_mov_b64_e32 v[94:95], v[174:175]
	v_mov_b64_e32 v[96:97], v[176:177]
	v_mov_b64_e32 v[98:99], v[178:179]
	v_mov_b64_e32 v[100:101], v[180:181]
	v_mov_b64_e32 v[102:103], v[182:183]
	v_mov_b64_e32 v[112:113], v[184:185]
	v_mov_b64_e32 v[114:115], v[186:187]
	s_waitcnt vmcnt(7)
	v_pk_mul_f32 v[88:89], v[40:41], v[88:89] op_sel_hi:[0,1]
	s_waitcnt vmcnt(6)
	v_pk_mul_f32 v[74:75], v[40:41], v[74:75] op_sel_hi:[0,1]
	s_waitcnt vmcnt(5)
	v_pk_mul_f32 v[60:61], v[40:41], v[66:67] op_sel_hi:[0,1]
	s_waitcnt vmcnt(4)
	v_pk_mul_f32 v[42:43], v[40:41], v[82:83] op_sel_hi:[0,1]
	v_pk_mul_f32 v[52:53], v[40:41], v[84:85] op_sel_hi:[0,1]
	v_pk_mul_f32 v[66:67], v[40:41], v[68:69] op_sel_hi:[0,1]
	v_pk_mul_f32 v[82:83], v[40:41], v[76:77] op_sel_hi:[0,1]
	v_pk_mul_f32 v[40:41], v[40:41], v[90:91] op_sel_hi:[0,1]
	s_waitcnt vmcnt(3)
	v_pk_mul_f32 v[92:93], v[38:39], v[92:93] op_sel_hi:[0,1]
	s_waitcnt vmcnt(2)
	v_pk_mul_f32 v[96:97], v[38:39], v[96:97] op_sel_hi:[0,1]
	s_waitcnt vmcnt(1)
	v_pk_mul_f32 v[84:85], v[38:39], v[100:101] op_sel_hi:[0,1]
	s_waitcnt vmcnt(0)
	v_pk_mul_f32 v[68:69], v[38:39], v[112:113] op_sel_hi:[0,1]
	v_pk_mul_f32 v[76:77], v[38:39], v[114:115] op_sel_hi:[0,1]
	v_pk_mul_f32 v[90:91], v[38:39], v[102:103] op_sel_hi:[0,1]
	v_pk_mul_f32 v[98:99], v[38:39], v[98:99] op_sel_hi:[0,1]
	v_pk_mul_f32 v[38:39], v[38:39], v[94:95] op_sel_hi:[0,1]
	v_lshlrev_b32_e32 v94, 16, v33
	v_and_b32_e32 v95, 0xffff0000, v33
	v_pk_fma_f32 v[78:79], v[78:79], v[94:95], 0 op_sel_hi:[1,1,0]
	v_lshlrev_b32_e32 v94, 16, v29
	v_and_b32_e32 v95, 0xffff0000, v29
	v_pk_fma_f32 v[78:79], v[86:87], v[94:95], v[78:79]
	v_lshlrev_b32_e32 v86, 16, v25
	v_and_b32_e32 v87, 0xffff0000, v25
	v_pk_fma_f32 v[40:41], v[40:41], v[86:87], v[78:79]
	v_lshlrev_b32_e32 v78, 16, v21
	v_and_b32_e32 v79, 0xffff0000, v21
	v_pk_fma_f32 v[38:39], v[38:39], v[78:79], v[40:41]
	v_lshlrev_b32_e32 v78, 16, v32
	v_and_b32_e32 v79, 0xffff0000, v32
	v_pk_fma_f32 v[32:33], v[70:71], v[78:79], 0 op_sel_hi:[1,1,0]
	v_lshlrev_b32_e32 v70, 16, v28
	v_and_b32_e32 v71, 0xffff0000, v28
	v_pk_fma_f32 v[28:29], v[80:81], v[70:71], v[32:33]
	v_lshlrev_b32_e32 v32, 16, v24
	v_and_b32_e32 v33, 0xffff0000, v24
	v_pk_fma_f32 v[24:25], v[88:89], v[32:33], v[28:29]
	v_lshlrev_b32_e32 v28, 16, v20
	v_and_b32_e32 v29, 0xffff0000, v20
	v_pk_fma_f32 v[20:21], v[92:93], v[28:29], v[24:25]
	v_lshlrev_b32_e32 v28, 16, v31
	v_and_b32_e32 v29, 0xffff0000, v31
	v_pk_fma_f32 v[28:29], v[62:63], v[28:29], 0 op_sel_hi:[1,1,0]
	v_lshlrev_b32_e32 v62, 16, v30
	v_and_b32_e32 v63, 0xffff0000, v30
	v_pk_fma_f32 v[30:31], v[56:57], v[62:63], 0 op_sel_hi:[1,1,0]
	v_lshlrev_b32_e32 v56, 16, v26
	v_and_b32_e32 v57, 0xffff0000, v26
	v_lshlrev_b32_e32 v32, 16, v27
	v_and_b32_e32 v33, 0xffff0000, v27
	v_pk_fma_f32 v[26:27], v[64:65], v[56:57], v[30:31]
	v_lshlrev_b32_e32 v30, 16, v22
	v_and_b32_e32 v31, 0xffff0000, v22
	v_pk_fma_f32 v[28:29], v[72:73], v[32:33], v[28:29]
	v_lshlrev_b32_e32 v32, 16, v23
	v_and_b32_e32 v33, 0xffff0000, v23
	v_pk_fma_f32 v[22:23], v[74:75], v[30:31], v[26:27]
	v_lshlrev_b32_e32 v26, 16, v18
	v_and_b32_e32 v27, 0xffff0000, v18
	v_pk_fma_f32 v[28:29], v[82:83], v[32:33], v[28:29]
	v_lshlrev_b32_e32 v32, 16, v19
	v_and_b32_e32 v33, 0xffff0000, v19
	v_pk_fma_f32 v[18:19], v[96:97], v[26:27], v[22:23]
	v_lshlrev_b32_e32 v26, 16, v15
	v_and_b32_e32 v27, 0xffff0000, v15
	v_pk_fma_f32 v[26:27], v[50:51], v[26:27], 0 op_sel_hi:[1,1,0]
	v_lshlrev_b32_e32 v50, 16, v14
	v_and_b32_e32 v51, 0xffff0000, v14
	v_mul_f32_e32 v16, 0xbfb8aa3b, v39
	v_lshlrev_b32_e32 v30, 16, v11
	v_and_b32_e32 v31, 0xffff0000, v11
	v_pk_fma_f32 v[14:15], v[48:49], v[50:51], 0 op_sel_hi:[1,1,0]
	v_lshlrev_b32_e32 v48, 16, v10
	v_and_b32_e32 v49, 0xffff0000, v10
	v_exp_f32_e32 v16, v16
	v_pk_fma_f32 v[26:27], v[58:59], v[30:31], v[26:27]
	v_lshlrev_b32_e32 v30, 16, v7
	v_and_b32_e32 v31, 0xffff0000, v7
	v_pk_fma_f32 v[10:11], v[54:55], v[48:49], v[14:15]
	v_lshlrev_b32_e32 v14, 16, v6
	v_and_b32_e32 v15, 0xffff0000, v6
	v_pk_fma_f32 v[26:27], v[66:67], v[30:31], v[26:27]
	v_lshlrev_b32_e32 v30, 16, v3
	v_and_b32_e32 v31, 0xffff0000, v3
	v_pk_fma_f32 v[6:7], v[60:61], v[14:15], v[10:11]
	v_lshlrev_b32_e32 v10, 16, v2
	v_and_b32_e32 v11, 0xffff0000, v2
	v_pk_fma_f32 v[26:27], v[90:91], v[30:31], v[26:27]
	v_pk_fma_f32 v[6:7], v[84:85], v[10:11], v[6:7]
	v_mul_f32_e32 v3, 0xbfb8aa3b, v27
	v_mul_f32_e32 v2, 0xbfb8aa3b, v7
	v_add_f32_e32 v16, 1.0, v16
	v_exp_f32_e32 v3, v3
	v_exp_f32_e32 v2, v2
	v_rcp_f32_e32 v41, v16
	v_mul_f32_e32 v16, 0xbfb8aa3b, v38
	v_exp_f32_e32 v16, v16
	v_add_f32_e32 v3, 1.0, v3
	v_add_f32_e32 v2, 1.0, v2
	v_rcp_f32_e32 v31, v3
	v_mul_f32_e32 v3, 0xbfb8aa3b, v26
	v_rcp_f32_e32 v11, v2
	v_mul_f32_e32 v2, 0xbfb8aa3b, v6
	v_add_f32_e32 v16, 1.0, v16
	v_exp_f32_e32 v3, v3
	v_exp_f32_e32 v2, v2
	v_rcp_f32_e32 v40, v16
	v_mul_f32_e32 v16, 0xbfb8aa3b, v21
	v_exp_f32_e32 v16, v16
	v_add_f32_e32 v3, 1.0, v3
	v_add_f32_e32 v2, 1.0, v2
	v_rcp_f32_e32 v30, v3
	v_rcp_f32_e32 v10, v2
	v_lshlrev_b32_e32 v2, 16, v13
	v_and_b32_e32 v3, 0xffff0000, v13
	v_add_f32_e32 v16, 1.0, v16
	v_pk_fma_f32 v[2:3], v[36:37], v[2:3], 0 op_sel_hi:[1,1,0]
	v_lshlrev_b32_e32 v14, 16, v9
	v_and_b32_e32 v15, 0xffff0000, v9
	v_rcp_f32_e32 v25, v16
	v_mul_f32_e32 v16, 0xbfb8aa3b, v20
	v_pk_fma_f32 v[2:3], v[46:47], v[14:15], v[2:3]
	v_lshlrev_b32_e32 v14, 16, v5
	v_and_b32_e32 v15, 0xffff0000, v5
	v_exp_f32_e32 v16, v16
	v_pk_fma_f32 v[2:3], v[52:53], v[14:15], v[2:3]
	v_lshlrev_b32_e32 v14, 16, v1
	v_and_b32_e32 v15, 0xffff0000, v1
	v_pk_fma_f32 v[2:3], v[76:77], v[14:15], v[2:3]
	v_add_f32_e32 v16, 1.0, v16
	v_mul_f32_e32 v1, 0xbfb8aa3b, v3
	v_exp_f32_e32 v1, v1
	v_pk_fma_f32 v[28:29], v[98:99], v[32:33], v[28:29]
	v_rcp_f32_e32 v24, v16
	v_mul_f32_e32 v16, 0xbfb8aa3b, v29
	v_exp_f32_e32 v16, v16
	v_add_f32_e32 v1, 1.0, v1
	v_rcp_f32_e32 v15, v1
	v_mul_f32_e32 v1, 0xbfb8aa3b, v2
	v_exp_f32_e32 v1, v1
	v_add_f32_e32 v16, 1.0, v16
	v_lshlrev_b32_e32 v36, 16, v12
	v_and_b32_e32 v37, 0xffff0000, v12
	v_rcp_f32_e32 v33, v16
	v_mul_f32_e32 v16, 0xbfb8aa3b, v28
	v_pk_fma_f32 v[12:13], v[34:35], v[36:37], 0 op_sel_hi:[1,1,0]
	v_lshlrev_b32_e32 v34, 16, v8
	v_and_b32_e32 v35, 0xffff0000, v8
	v_exp_f32_e32 v16, v16
	v_pk_fma_f32 v[8:9], v[44:45], v[34:35], v[12:13]
	v_lshlrev_b32_e32 v12, 16, v4
	v_and_b32_e32 v13, 0xffff0000, v4
	v_add_f32_e32 v1, 1.0, v1
	v_pk_fma_f32 v[4:5], v[42:43], v[12:13], v[8:9]
	v_lshlrev_b32_e32 v8, 16, v0
	v_and_b32_e32 v9, 0xffff0000, v0
	v_rcp_f32_e32 v14, v1
	v_pk_fma_f32 v[0:1], v[68:69], v[8:9], v[4:5]
	v_add_f32_e32 v16, 1.0, v16
	v_mul_f32_e32 v4, 0xbfb8aa3b, v1
	v_exp_f32_e32 v4, v4
	v_rcp_f32_e32 v32, v16
	v_mul_f32_e32 v16, 0xbfb8aa3b, v19
	v_exp_f32_e32 v16, v16
	v_add_f32_e32 v4, 1.0, v4
	v_rcp_f32_e32 v5, v4
	v_mul_f32_e32 v4, 0xbfb8aa3b, v0
	v_add_f32_e32 v16, 1.0, v16
	v_exp_f32_e32 v4, v4
	v_rcp_f32_e32 v23, v16
	v_mul_f32_e32 v16, 0xbfb8aa3b, v18
	v_exp_f32_e32 v16, v16
	v_add_f32_e32 v4, 1.0, v4
	v_rcp_f32_e32 v4, v4
	v_pk_mul_f32 v[2:3], v[2:3], v[14:15]
	v_add_f32_e32 v16, 1.0, v16
	v_rcp_f32_e32 v22, v16
	v_pk_mul_f32 v[0:1], v[0:1], v[4:5]
	ds_write_b128 v110, v[0:3] offset:34816
	v_pk_mul_f32 v[0:1], v[6:7], v[10:11]
	v_pk_mul_f32 v[2:3], v[26:27], v[30:31]
	ds_write_b128 v110, v[0:3] offset:34832
	v_pk_mul_f32 v[0:1], v[18:19], v[22:23]
	v_pk_mul_f32 v[2:3], v[28:29], v[32:33]
	ds_write_b128 v110, v[0:3] offset:34848
	v_pk_mul_f32 v[0:1], v[20:21], v[24:25]
	v_pk_mul_f32 v[2:3], v[38:39], v[40:41]
	v_lshl_add_u32 v44, v106, 2, 0
	ds_write_b128 v110, v[0:3] offset:34864
	s_and_saveexec_b64 s[8:9], vcc
	s_cbranch_execz .LBB0_763
	v_or_b32_e32 v0, s5, v106
	v_ashrrev_i32_e32 v1, 31, v0
	v_lshlrev_b64 v[0:1], 5, v[0:1]
	v_lshl_add_u64 v[0:1], s[42:43], 0, v[0:1]
	s_lshl_b32 s52, s37, 2
	v_lshl_add_u64 v[0:1], v[0:1], 0, s[52:53]
	flat_load_dword v2, v[0:1] offset:16
	s_nop 0
	flat_load_dword v0, v[0:1]
	s_mov_b32 s38, 0
	s_ashr_i32 s39, s38, 31
	s_lshl_b64 s[38:39], s[38:39], 3
	s_add_u32 s38, s0, s38
	s_addc_u32 s39, s1, s39
	s_load_dwordx2 s[38:39], s[38:39], 0x98
	s_or_b32 s48, s37, s35
	s_ashr_i32 s49, s48, 31
	s_lshl_b64 s[48:49], s[48:49], 2
	s_mov_b32 s2, 0xbfb8aa3b
	s_waitcnt lgkmcnt(0)
	s_add_u32 s38, s38, s48
	s_addc_u32 s39, s39, s49
	global_load_dword v1, v17, s[38:39]
	s_mov_b32 s38, 0
	s_ashr_i32 s39, s38, 31
	s_lshl_b64 s[38:39], s[38:39], 3
	s_add_u32 s38, s0, s38
	s_addc_u32 s39, s1, s39
	s_load_dwordx2 s[38:39], s[38:39], 0xa0
	s_waitcnt lgkmcnt(0)
	s_add_u32 s38, s38, s48
	s_addc_u32 s39, s39, s49
	global_load_dword v3, v17, s[38:39]
	s_waitcnt vmcnt(0)
	v_mul_f32_e32 v0, 0xbfb8aa3b, v0
	v_exp_f32_e32 v0, v0
	v_mul_f32_e32 v1, 0x3fb8aa3b, v1
	v_exp_f32_e32 v1, v1
	v_add_f32_e32 v0, 1.0, v0
	v_rcp_f32_e32 v0, v0
	v_add_f32_e32 v2, v2, v3
	v_max_f32_e32 v4, 0, v2
	v_mul_f32_e64 v2, |v2|, s2
	v_exp_f32_e32 v5, v2
	s_mov_b32 s2, 0x3f2aaaab
	v_add_f32_e32 v6, 1.0, v5
	v_add_f32_e32 v2, -1.0, v6
	v_sub_f32_e32 v3, v2, v6
	v_add_f32_e32 v3, 1.0, v3
	v_sub_f32_e32 v2, v5, v2
	v_add_f32_e32 v7, v2, v3
	v_frexp_mant_f32_e32 v2, v6
	v_cmp_gt_f32_e32 vcc, s2, v2
	v_cvt_f64_f32_e32 v[2:3], v6
	v_frexp_exp_i32_f64_e32 v2, v[2:3]
	v_subbrev_co_u32_e32 v2, vcc, 0, v2, vcc
	v_sub_u32_e32 v3, 0, v2
	v_ldexp_f32 v6, v6, v3
	v_ldexp_f32 v3, v7, v3
	v_add_f32_e32 v7, -1.0, v6
	v_add_f32_e32 v8, 1.0, v7
	v_sub_f32_e32 v8, v6, v8
	v_add_f32_e32 v8, v3, v8
	v_add_f32_e32 v9, v7, v8
	v_sub_f32_e32 v7, v9, v7
	v_sub_f32_e32 v7, v8, v7
	v_add_f32_e32 v8, 1.0, v6
	v_add_f32_e32 v10, -1.0, v8
	v_sub_f32_e32 v6, v6, v10
	v_add_f32_e32 v3, v3, v6
	v_add_f32_e32 v6, v8, v3
	v_sub_f32_e32 v8, v6, v8
	v_sub_f32_e32 v3, v3, v8
	v_rcp_f32_e32 v8, v6
	v_cvt_f32_i32_e32 v2, v2
	s_mov_b32 s2, 0x3f317218
	v_mul_f32_e32 v10, v9, v8
	v_mul_f32_e32 v11, v6, v10
	v_fma_f32 v12, v10, v6, -v11
	v_fmac_f32_e32 v12, v10, v3
	v_add_f32_e32 v13, v11, v12
	v_sub_f32_e32 v14, v9, v13
	v_sub_f32_e32 v9, v9, v14
	v_sub_f32_e32 v11, v13, v11
	v_sub_f32_e32 v9, v9, v13
	v_add_f32_e32 v7, v7, v9
	v_sub_f32_e32 v9, v11, v12
	v_add_f32_e32 v7, v9, v7
	v_add_f32_e32 v9, v14, v7
	v_mul_f32_e32 v11, v8, v9
	v_mul_f32_e32 v12, v6, v11
	v_fma_f32 v6, v11, v6, -v12
	v_fmac_f32_e32 v6, v11, v3
	v_sub_f32_e32 v3, v14, v9
	v_add_f32_e32 v3, v7, v3
	v_add_f32_e32 v7, v12, v6
	v_sub_f32_e32 v13, v9, v7
	v_sub_f32_e32 v9, v9, v13
	v_sub_f32_e32 v12, v7, v12
	v_sub_f32_e32 v7, v9, v7
	v_add_f32_e32 v3, v3, v7
	v_sub_f32_e32 v6, v12, v6
	v_add_f32_e32 v3, v6, v3
	v_add_f32_e32 v6, v10, v11
	v_add_f32_e32 v3, v13, v3
	v_sub_f32_e32 v7, v6, v10
	v_mul_f32_e32 v3, v8, v3
	v_sub_f32_e32 v7, v11, v7
	v_add_f32_e32 v3, v7, v3
	v_mul_f32_e32 v10, 0x3f317218, v2
	v_add_f32_e32 v7, v6, v3
	v_fma_f32 v11, v2, s2, -v10
	v_mul_f32_e32 v8, v7, v7
	v_fmac_f32_e32 v11, 0xb102e308, v2
	v_sub_f32_e32 v2, v7, v6
	v_fmamk_f32 v9, v8, 0x3e9b6dac, v232
	v_sub_f32_e32 v2, v3, v2
	v_add_f32_e32 v3, v10, v11
	v_fmaak_f32 v9, v8, v9, 0x3f2aaada
	v_sub_f32_e32 v6, v3, v10
	v_ldexp_f32 v10, v7, 1
	v_mul_f32_e32 v7, v7, v8
	v_mul_f32_e32 v7, v7, v9
	v_add_f32_e32 v8, v10, v7
	v_sub_f32_e32 v9, v8, v10
	v_ldexp_f32 v2, v2, 1
	v_sub_f32_e32 v7, v7, v9
	v_add_f32_e32 v2, v2, v7
	v_add_f32_e32 v7, v8, v2
	v_sub_f32_e32 v8, v7, v8
	v_sub_f32_e32 v2, v2, v8
	v_add_f32_e32 v8, v3, v7
	v_sub_f32_e32 v9, v8, v3
	v_sub_f32_e32 v10, v8, v9
	v_sub_f32_e32 v6, v11, v6
	v_sub_f32_e32 v3, v3, v10
	v_sub_f32_e32 v7, v7, v9
	v_add_f32_e32 v3, v7, v3
	v_add_f32_e32 v7, v6, v2
	v_sub_f32_e32 v9, v7, v6
	v_sub_f32_e32 v10, v7, v9
	v_sub_f32_e32 v6, v6, v10
	v_sub_f32_e32 v2, v2, v9
	v_add_f32_e32 v3, v7, v3
	v_add_f32_e32 v2, v2, v6
	v_add_f32_e32 v6, v8, v3
	v_sub_f32_e32 v7, v6, v8
	v_sub_f32_e32 v3, v3, v7
	v_add_f32_e32 v2, v2, v3
	s_mov_b32 s2, 0x7f800000
	v_add_f32_e32 v2, v6, v2
	v_cmp_neq_f32_e32 vcc, s2, v5
	s_mov_b32 s2, 0x33800000
	s_nop 0
	v_cndmask_b32_e32 v2, v236, v2, vcc
	v_cmp_ngt_f32_e32 vcc, -1.0, v5
	s_nop 1
	v_cndmask_b32_e32 v2, v237, v2, vcc
	v_cmp_neq_f32_e32 vcc, -1.0, v5
	s_nop 1
	v_cndmask_b32_e32 v2, v238, v2, vcc
	v_cmp_lt_f32_e64 vcc, |v5|, s2
	s_nop 1
	v_cndmask_b32_e32 v2, v2, v5, vcc
	v_add_f32_e32 v2, v4, v2
	v_add_u32_e32 v4, -1, v234
	v_cmp_lt_i32_e32 vcc, v4, v111
	v_mul_f32_e64 v3, v2, -v1
	s_nop 0
	v_cndmask_b32_e32 v4, v4, v234, vcc
	v_lshlrev_b32_e32 v4, 2, v4
	ds_bpermute_b32 v4, v4, v3
	v_cmp_eq_u32_e32 vcc, 0, v106
	s_waitcnt lgkmcnt(0)
	v_fma_f32 v1, v2, -v1, v4
	v_add_u32_e32 v2, -2, v234
	v_cndmask_b32_e32 v1, v1, v3, vcc
	v_cmp_lt_i32_e32 vcc, v2, v111
	v_add_u32_e32 v3, 0x1cc00, v44
	s_nop 0
	v_cndmask_b32_e32 v2, v2, v234, vcc
	v_lshlrev_b32_e32 v2, 2, v2
	ds_bpermute_b32 v2, v2, v1
	v_cmp_gt_u32_e32 vcc, 2, v106
	s_waitcnt lgkmcnt(0)
	v_add_f32_e32 v2, v1, v2
	v_cndmask_b32_e32 v1, v2, v1, vcc
	v_add_u32_e32 v2, -4, v234
	v_cmp_lt_i32_e32 vcc, v2, v111
	s_nop 1
	v_cndmask_b32_e32 v2, v2, v234, vcc
	v_lshlrev_b32_e32 v2, 2, v2
	ds_bpermute_b32 v2, v2, v1
	v_cmp_gt_u32_e32 vcc, 4, v106
	s_waitcnt lgkmcnt(0)
	v_add_f32_e32 v2, v1, v2
	v_cndmask_b32_e32 v1, v2, v1, vcc
	v_add_u32_e32 v2, -8, v234
	v_cmp_lt_i32_e32 vcc, v2, v111
	s_nop 1
	v_cndmask_b32_e32 v2, v2, v234, vcc
	v_lshlrev_b32_e32 v2, 2, v2
	ds_bpermute_b32 v2, v2, v1
	v_cmp_gt_u32_e32 vcc, 8, v106
	s_waitcnt lgkmcnt(0)
	v_add_f32_e32 v2, v1, v2
	v_cndmask_b32_e32 v1, v2, v1, vcc
	v_add_u32_e32 v2, -16, v234
	v_cmp_lt_i32_e32 vcc, v2, v111
	s_nop 1
	v_cndmask_b32_e32 v2, v2, v234, vcc
	v_lshlrev_b32_e32 v2, 2, v2
	ds_bpermute_b32 v2, v2, v1
	v_cmp_gt_u32_e32 vcc, 16, v106
	s_waitcnt lgkmcnt(0)
	v_add_f32_e32 v2, v1, v2
	v_cndmask_b32_e32 v2, v2, v1, vcc
	v_subrev_u32_e32 v1, 32, v234
	v_cmp_lt_i32_e32 vcc, v1, v111
	s_nop 1
	v_cndmask_b32_e32 v1, v1, v234, vcc
	v_lshlrev_b32_e32 v1, 2, v1
	ds_bpermute_b32 v1, v1, v2
	v_cmp_gt_u32_e32 vcc, 32, v106
	s_waitcnt lgkmcnt(0)
	v_add_f32_e32 v1, v2, v1
	v_cndmask_b32_e32 v2, v1, v2, vcc
	ds_write_b32 v3, v2
	v_add_u32_e32 v2, 0x1cd00, v44
	v_cmp_eq_u32_e32 vcc, 63, v106
	ds_write_b32 v2, v0
	s_and_b64 exec, exec, vcc
	s_cbranch_execz .LBB0_763
	v_mul_f32_e32 v0, 0x3fb8aa3b, v1
	v_exp_f32_e32 v2, v0
	v_mov_b64_e32 v[0:1], s[92:93]
	flat_store_dword v[0:1], v2
